# placement check moved into the first grid barrier (atomic OR returns other XCC bits); seam 1-2 also a 32-workgroup barrier with the RWKV-prep token chunks re-dealt to the workgroup's own group rows
# speedup vs baseline: 1.0072x; 1.0072x over previous
.LBB0_1467:
	s_cmp_gt_i32 s87, 1
	s_cselect_b64 s[2:3], -1, 0
	s_and_b64 s[0:1], s[6:7], s[2:3]
	s_andn2_b64 vcc, exec, s[0:1]
	s_cbranch_vccnz .LBB0_1521
	s_waitcnt vmcnt(0)
	s_waitcnt lgkmcnt(0)
	s_barrier
	s_mov_b64 s[0:1], exec
	v_readlane_b32 s4, v251, 1
	v_readlane_b32 s5, v251, 2
	s_and_b64 s[4:5], s[0:1], s[4:5]
	s_mov_b64 exec, s[4:5]
	s_cbranch_execz .LBB0_1520
	s_and_b32 s4, s90, 7
	s_lshl_b32 s4, s4, 2
	s_add_i32 s4, s4, 0x3e40
	s_lshl_b32 s5, 1, s84
	v_mov_b32_e32 v0, s4
	v_mov_b32_e32 v2, s5
	global_atomic_or v0, v0, v2, s[96:97] sc0
	s_waitcnt vmcnt(0)
	v_readfirstlane_b32 s4, v0
	s_andn2_b32 s4, s4, s5
	s_cmp_lg_u32 s4, 0
	s_cselect_b32 s4, 1, 0
	s_cmp_lg_u32 s92, 0x100
	s_cselect_b32 s5, 1, 0
	s_or_b32 s4, s4, s5
	s_cmp_eq_u32 s4, 0
	s_cbranch_scc1 .Lplc_ok
	v_mov_b32_e32 v0, 0x3e00
	v_mov_b32_e32 v2, 1
	global_atomic_add v0, v2, s[96:97]
	s_waitcnt vmcnt(0)

.LBB0_1696:
	s_cmp_gt_i32 s87, 2
	s_cselect_b64 s[2:3], -1, 0
	s_and_b64 s[0:1], s[0:1], s[2:3]
	s_andn2_b64 vcc, exec, s[0:1]
	s_cbranch_vccnz .LBB0_1750
	s_waitcnt vmcnt(0)
	s_waitcnt vmcnt(0) lgkmcnt(0)
	s_barrier
	s_mov_b64 s[0:1], exec
	v_readlane_b32 s4, v251, 1
	v_readlane_b32 s5, v251, 2
	s_and_b64 s[4:5], s[0:1], s[4:5]
	s_mov_b64 exec, s[4:5]
	s_cbranch_execz .LBB0_1749
	s_waitcnt vmcnt(0) expcnt(0) lgkmcnt(0)
	buffer_inv sc1
	s_and_b32 s4, s90, 7
	s_lshl_b32 s4, s4, 8
	s_add_i32 s4, s4, 0x3600
	v_mov_b32_e32 v0, s4
	v_mov_b32_e32 v2, 1
	global_atomic_add v0, v0, v2, s[96:97] sc0
	s_nop 0
	v_mov_b32_e32 v2, 0x3e00
	global_load_dword v2, v2, s[96:97] sc1
	s_waitcnt vmcnt(0)
	v_readfirstlane_b32 s5, v2
	v_readfirstlane_b32 vcc_lo, v0
	s_cmp_lg_u32 s5, 0
	s_cbranch_scc1 .Lgb_orig5
	s_or_b32 s5, vcc_lo, 31
	s_cmp_eq_u32 s5, vcc_lo
	s_cbranch_scc1 .Lgb_done5
	s_add_i32 s5, s5, 1
	s_mov_b32 vcc_hi, 0
	v_mov_b32_e32 v0, s4

.LBB0_1750:
	s_cmp_lt_i32 s86, 3
	s_cselect_b64 s[4:5], -1, 0
	s_and_b64 s[0:1], s[4:5], s[2:3]
	s_andn2_b64 vcc, exec, s[0:1]
	s_cbranch_vccnz .LBB0_1778
	s_cmpk_gt_i32 s90, 0xff
	s_cbranch_scc1 .LBB0_1778
	v_lshrrev_b32_e32 v2, 1, v153
	v_and_b32_e32 v2, 24, v2
	v_lshlrev_b32_e32 v4, 2, v2
	v_mov_b32_e32 v117, 0
	v_or_b32_e32 v116, 0x1800, v4
	v_lshl_add_u64 v[118:119], s[60:61], 0, v[116:117]
	v_or_b32_e32 v116, 0x1880, v4
	v_lshl_add_u64 v[120:121], s[60:61], 0, v[116:117]
	v_or_b32_e32 v116, 0x1900, v4
	v_lshl_add_u64 v[122:123], s[60:61], 0, v[116:117]
	v_or_b32_e32 v116, 0x1980, v4
	v_readlane_b32 s1, v251, 7
	v_lshl_add_u64 v[124:125], s[60:61], 0, v[116:117]
	v_or_b32_e32 v116, 0x1a00, v4
	s_lshl_b32 s0, s1, 4
	s_lshl_b32 s1, s1, 13
	v_lshl_add_u64 v[126:127], s[60:61], 0, v[116:117]
	v_or_b32_e32 v116, 0x1a80, v4
	s_movk_i32 s3, 0x200
	s_add_u32 s6, s96, 0x7000000
	v_lshl_add_u64 v[128:129], s[60:61], 0, v[116:117]
	v_or_b32_e32 v116, 0x1b00, v4
	v_subrev_co_u32_e32 v189, vcc, s3, v153
	s_addc_u32 s7, s97, 0
	s_add_i32 s2, s1, 0
	v_lshl_add_u64 v[130:131], s[60:61], 0, v[116:117]
	v_or_b32_e32 v116, 0x1b80, v4
	v_and_b32_e32 v4, 7, v153
	v_lshrrev_b32_e32 v5, 3, v153
	s_movk_i32 s1, 0x90
	v_lshrrev_b32_e32 v6, 3, v189
	v_lshlrev_b32_e32 v11, 4, v4
	v_mad_u32_u24 v14, v5, s1, 0
	v_lshlrev_b32_e32 v15, 1, v153
	v_and_b32_e32 v4, 3, v153
	v_mul_lo_u32 v17, v6, s1
	v_lshrrev_b32_e32 v8, 4, v189
	s_movk_i32 s1, 0x110
	v_lshl_add_u64 v[132:133], s[60:61], 0, v[116:117]
	v_and_or_b32 v9, v15, 24, v4
	v_mul_lo_u32 v18, v8, s1
	v_add_u32_e32 v21, 0x200, v153
	v_lshlrev_b32_e32 v116, 2, v153
	s_mul_i32 s1, s90, 0x1010
	s_and_b32 s1, s1, 0x7f80
	v_and_b32_e32 v1, 15, v153
	v_lshrrev_b32_e32 v21, 4, v21
	v_mul_u32_u24_e32 v23, 0x90, v9
	v_mul_u32_u24_e32 v24, 0x110, v9
	v_add_u32_e32 v9, 0, v116
	s_add_i32 s1, s1, s0
	v_or_b32_e32 v188, s0, v1
	v_lshlrev_b32_e32 v7, 4, v1
	v_lshrrev_b32_e32 v19, 4, v153
	v_add_u32_e32 v190, 0x9000, v9
	v_add_u32_e32 v192, 0xb000, v9
	v_lshl_add_u64 v[134:135], s[60:61], 0, v[116:117]
	v_lshl_or_b32 v116, v5, 7, v11
	v_or_b32_e32 v140, s1, v1
	v_lshlrev_b32_e32 v1, 8, v21
	s_mov_b32 s0, 0x2920000
	v_mov_b32_e32 v9, v117
	v_mov_b64_e32 v[136:137], v[116:117]
	v_or3_b32 v116, v1, v7, s0
	v_lshlrev_b32_e32 v1, 8, v19
	v_lshlrev_b64 v[8:9], 8, v[8:9]
	v_add_u32_e32 v10, 0, v7
	v_mov_b64_e32 v[142:143], v[116:117]
	v_or3_b32 v116, v1, v7, s0
	v_or_b32_e32 v8, v8, v7
	v_mov_b32_e32 v7, v117
	s_mov_b64 s[0:1], 0x2920000
	v_lshlrev_b64 v[6:7], 7, v[6:7]
	v_mul_u32_u24_e32 v13, 0x90, v5
	v_and_b32_e32 v4, 48, v153
	v_mov_b32_e32 v5, v117
	v_lshl_add_u64 v[146:147], v[8:9], 0, s[0:1]
	v_or_b32_e32 v6, v6, v11
	s_mov_b64 s[0:1], 0x2910000
	v_and_b32_e32 v1, 0x60, v15
	v_readlane_b32 s12, v251, 3
	v_lshlrev_b32_e32 v3, 4, v152
	v_and_b32_e32 v0, 0x1ff, v153
	v_add_u32_e32 v12, 0, v11
	v_add_u32_e32 v16, 0, v4
	v_mul_u32_u24_e32 v20, 0x110, v19
	v_mul_u32_u24_e32 v22, 0x110, v21
	v_lshl_add_u64 v[138:139], s[96:97], 0, v[4:5]
	v_lshl_add_u64 v[148:149], v[6:7], 0, s[0:1]
	v_add_u32_e32 v1, 0, v1
	v_readlane_b32 s13, v251, 4
	v_readlane_b32 s14, v251, 5
	v_readlane_b32 s15, v251, 6
	s_mov_b64 s[0:1], 0x7000440
	s_movk_i32 s22, 0x1ff
	s_xor_b64 s[8:9], vcc, -1
	v_lshrrev_b32_e32 v191, 9, v153
	s_lshl_b32 s23, s92, 7
	v_mov_b64_e32 v[144:145], v[116:117]
	v_add_u32_e32 v193, 0x9000, v1
	v_lshl_add_u64 v[150:151], s[14:15], 0, v[4:5]
	v_lshl_add_u64 v[154:155], v[138:139], 0, s[0:1]
	v_lshlrev_b32_e32 v116, 2, v0
	s_movk_i32 s24, 0x5ff
	s_mov_b64 s[10:11], 0x800
	s_movk_i32 s25, 0x4ff
	s_movk_i32 s26, 0xe00
	v_lshlrev_b32_e32 v156, 1, v2
	s_mov_b32 s27, 0xbfb8aa3b
	v_add_u32_e32 v194, v12, v17
	v_add_u32_e32 v195, v14, v11
	v_add_u32_e32 v196, v10, v18
	v_add_u32_e32 v197, v12, v13
	v_add_u32_e32 v198, v10, v20
	v_add_u32_e32 v199, v10, v22
	v_add_u32_e32 v200, v16, v23
	v_add_u32_e32 v201, v16, v24
	s_mov_b32 s28, 0x800000
	s_mov_b32 s29, 0x3f317217
	s_mov_b32 s30, 0x7f800000
	s_brev_b32 s31, 64
	s_mov_b32 s33, 0x6000000
	s_brev_b32 s34, 32
	s_mov_b32 s35, 0x1dd00000
	s_waitcnt lgkmcnt(0)
	s_mov_b32 s38, 0x3000000
	s_mov_b32 s39, 0x5000000
	s_mov_b64 s[12:13], 0x2000
	s_mov_b64 s[14:15], 0x4000
	v_mov_b32_e32 v203, 0xfffff200
	v_add_u32_e32 v204, s2, v3
	v_mov_b32_e32 v205, 0x41b17218
	s_mul_i32 s40, s90, 0x1010
	s_and_b32 s40, s40, 0x7f80
	s_lshr_b32 s40, s40, 7
	s_branch .LBB0_1754
